# hyena FFT conv: skip term folded into the spectrum product (U*(K+skip/N)); per-pair store segment reduced to LDS read + bf16 pack + store
# speedup vs baseline: 1.0268x; 1.0039x over previous
.LBB0_309:
	v_mul_f32_e32 v252, 0x38800000, v82
	v_mov_b32_e32 v253, v252
	s_lshl_b32 s33, s80, 15
	s_add_u32 s90, s52, s33
	s_addc_u32 s91, s73, 0
	v_lshl_add_u64 v[104:105], v[62:63], 1, s[90:91]
	s_barrier
	global_load_dwordx4 v[0:3], v[104:105], off
	v_mov_b32_e32 v16, 0
	v_lshl_add_u64 v[110:111], v[68:69], 1, s[90:91]
	v_mov_b32_e32 v17, 0
	v_mov_b32_e32 v244, 0
	s_and_saveexec_b64 s[40:41], s[12:13]
	s_cbranch_execz .LBB0_311
	global_load_ushort v244, v[110:111], off offset:-2
	s_nop 0
	s_nop 0

.LBB0_353:
	v_ashrrev_i32_e32 v0, 3, v42
	v_add_u32_e32 v1, 0x200, v42
	v_and_b32_e32 v0, -16, v0
	v_ashrrev_i32_e32 v1, 3, v1
	v_and_b32_e32 v1, -16, v1
	v_lshl_add_u32 v43, v0, 3, v196
	v_add_u32_e32 v32, v0, v197
	v_add_u32_e32 v34, v1, v197
	v_lshl_add_u32 v44, v1, 3, v196
	ds_read2_b64 v[46:49], v43 offset1:1
	ds_read2_b64 v[20:23], v44 offset1:1
	ds_read2_b64 v[50:53], v43 offset0:2 offset1:3
	ds_read2_b64 v[12:15], v44 offset0:2 offset1:3
	ds_read2_b64 v[136:139], v43 offset0:4 offset1:5
	ds_read2_b64 v[4:7], v44 offset0:4 offset1:5
	ds_read2_b64 v[140:143], v43 offset0:6 offset1:7
	ds_read2_b64 v[0:3], v44 offset0:6 offset1:7
	ds_read2_b64 v[144:147], v43 offset0:8 offset1:9
	ds_read2_b64 v[28:31], v44 offset0:8 offset1:9
	ds_read2_b64 v[148:151], v43 offset0:10 offset1:11
	ds_read2_b64 v[24:27], v44 offset0:10 offset1:11
	ds_read2_b64 v[152:155], v43 offset0:12 offset1:13
	ds_read2_b64 v[16:19], v44 offset0:12 offset1:13
	ds_read2_b64 v[156:159], v43 offset0:14 offset1:15
	ds_read2_b64 v[8:11], v44 offset0:14 offset1:15
	s_waitcnt lgkmcnt(7)
	v_pk_add_f32 v[38:39], v[46:47], v[144:145]
	v_pk_add_f32 v[36:37], v[46:47], v[144:145] neg_lo:[0,1] neg_hi:[0,1]
	v_pk_add_f32 v[46:47], v[48:49], v[146:147] neg_lo:[0,1] neg_hi:[0,1]
	v_pk_add_f32 v[40:41], v[48:49], v[146:147]
	v_pk_mul_f32 v[48:49], v[46:47], s[42:43] op_sel_hi:[0,1]
	s_mov_b32 s65, s42
	v_pk_fma_f32 v[46:47], v[46:47], s[64:65], v[48:49] op_sel:[1,0,0]
	s_waitcnt lgkmcnt(5)
	v_pk_add_f32 v[48:49], v[50:51], v[148:149]
	v_pk_add_f32 v[50:51], v[50:51], v[148:149] neg_lo:[0,1] neg_hi:[0,1]
	s_mov_b32 s66, s64
	v_mul_f32_e32 v54, 0x3f3504f3, v51
	v_pk_fma_f32 v[50:51], v[50:51], s[56:57], v[54:55] op_sel_hi:[0,1,0]
	v_pk_add_f32 v[54:55], v[52:53], v[150:151]
	v_pk_add_f32 v[52:53], v[52:53], v[150:151] neg_lo:[0,1] neg_hi:[0,1]
	s_mov_b32 s40, s42
	v_pk_mul_f32 v[144:145], v[52:53], s[66:67] op_sel_hi:[0,1]
	s_mov_b32 s41, s64
	v_pk_fma_f32 v[52:53], v[52:53], s[40:41], v[144:145] op_sel:[1,0,0]
	s_waitcnt lgkmcnt(3)
	v_pk_add_f32 v[144:145], v[136:137], v[152:153]
	v_pk_add_f32 v[136:137], v[136:137], v[152:153] neg_lo:[0,1] neg_hi:[0,1]
	s_mov_b32 s44, s43
	v_xor_b32_e32 v147, 0x80000000, v136
	v_mov_b32_e32 v146, v137
	v_pk_add_f32 v[136:137], v[138:139], v[154:155]
	v_pk_add_f32 v[138:139], v[138:139], v[154:155] neg_lo:[0,1] neg_hi:[0,1]
	s_mov_b32 s45, s67
	v_pk_mul_f32 v[148:149], v[138:139], s[44:45] op_sel_hi:[0,1]
	s_waitcnt lgkmcnt(1)
	v_pk_add_f32 v[150:151], v[142:143], v[158:159]
	v_pk_add_f32 v[142:143], v[142:143], v[158:159] neg_lo:[0,1] neg_hi:[0,1]
	s_mov_b32 s58, s67
	s_mov_b32 s59, s43
	v_pk_fma_f32 v[138:139], v[138:139], s[42:43], v[148:149] op_sel:[1,0,0]
	v_pk_add_f32 v[148:149], v[140:141], v[156:157]
	v_pk_add_f32 v[140:141], v[140:141], v[156:157] neg_lo:[0,1] neg_hi:[0,1]
	v_pk_mul_f32 v[152:153], v[142:143], s[58:59] op_sel_hi:[0,1]
	v_mul_f32_e32 v66, 0xbf3504f3, v140
	v_pk_fma_f32 v[142:143], v[142:143], s[66:67], v[152:153] op_sel:[1,0,0]
	v_pk_add_f32 v[152:153], v[38:39], v[144:145]
	v_pk_add_f32 v[38:39], v[38:39], v[144:145] neg_lo:[0,1] neg_hi:[0,1]
	v_pk_add_f32 v[144:145], v[40:41], v[136:137]
	v_pk_add_f32 v[40:41], v[40:41], v[136:137] neg_lo:[0,1] neg_hi:[0,1]
	v_pk_add_f32 v[136:137], v[48:49], v[148:149]
	v_pk_add_f32 v[48:49], v[48:49], v[148:149] neg_lo:[0,1] neg_hi:[0,1]
	v_pk_fma_f32 v[140:141], v[140:141], s[56:57], v[66:67] op_sel:[1,0,0] op_sel_hi:[1,1,0]
	v_mul_f32_e32 v66, 0x3f3504f3, v41
	v_xor_b32_e32 v149, 0x80000000, v48
	v_mov_b32_e32 v148, v49
	v_pk_add_f32 v[48:49], v[54:55], v[150:151]
	v_pk_add_f32 v[54:55], v[54:55], v[150:151] neg_lo:[0,1] neg_hi:[0,1]
	v_pk_fma_f32 v[40:41], v[40:41], s[56:57], v[66:67] op_sel_hi:[0,1,0]
	v_mul_f32_e32 v66, 0xbf3504f3, v54
	v_pk_add_f32 v[150:151], v[36:37], v[146:147]
	v_pk_add_f32 v[36:37], v[36:37], v[146:147] neg_lo:[0,1] neg_hi:[0,1]
	v_pk_add_f32 v[146:147], v[46:47], v[138:139]
	v_pk_add_f32 v[46:47], v[46:47], v[138:139] neg_lo:[0,1] neg_hi:[0,1]
	v_pk_add_f32 v[138:139], v[50:51], v[140:141]
	v_pk_add_f32 v[50:51], v[50:51], v[140:141] neg_lo:[0,1] neg_hi:[0,1]
	v_pk_fma_f32 v[54:55], v[54:55], s[56:57], v[66:67] op_sel:[1,0,0] op_sel_hi:[1,1,0]
	v_xor_b32_e32 v141, 0x80000000, v50
	v_mov_b32_e32 v140, v51
	v_pk_add_f32 v[50:51], v[52:53], v[142:143]
	v_pk_add_f32 v[52:53], v[52:53], v[142:143] neg_lo:[0,1] neg_hi:[0,1]
	v_pk_add_f32 v[142:143], v[152:153], v[136:137]
	v_pk_add_f32 v[136:137], v[152:153], v[136:137] neg_lo:[0,1] neg_hi:[0,1]
	v_pk_add_f32 v[152:153], v[144:145], v[48:49]
	v_pk_add_f32 v[48:49], v[144:145], v[48:49] neg_lo:[0,1] neg_hi:[0,1]
	v_mul_f32_e32 v66, 0x3f3504f3, v47
	v_xor_b32_e32 v145, 0x80000000, v48
	v_mov_b32_e32 v144, v49
	v_pk_add_f32 v[48:49], v[38:39], v[148:149]
	v_pk_add_f32 v[38:39], v[38:39], v[148:149] neg_lo:[0,1] neg_hi:[0,1]
	v_pk_add_f32 v[148:149], v[40:41], v[54:55]
	v_pk_fma_f32 v[46:47], v[46:47], s[56:57], v[66:67] op_sel_hi:[0,1,0]
	v_pk_add_f32 v[160:161], v[48:49], v[148:149]
	v_pk_add_f32 v[162:163], v[48:49], v[148:149] neg_lo:[0,1] neg_hi:[0,1]
	v_pk_add_f32 v[48:49], v[20:21], v[28:29]
	v_pk_add_f32 v[20:21], v[20:21], v[28:29] neg_lo:[0,1] neg_hi:[0,1]
	v_pk_add_f32 v[28:29], v[22:23], v[30:31]
	v_pk_add_f32 v[22:23], v[22:23], v[30:31] neg_lo:[0,1] neg_hi:[0,1]
	v_mul_f32_e32 v66, 0xbf3504f3, v52
	v_pk_mul_f32 v[30:31], v[22:23], s[42:43] op_sel_hi:[0,1]
	v_pk_fma_f32 v[22:23], v[22:23], s[64:65], v[30:31] op_sel:[1,0,0]
	v_pk_add_f32 v[30:31], v[12:13], v[24:25]
	v_pk_add_f32 v[12:13], v[12:13], v[24:25] neg_lo:[0,1] neg_hi:[0,1]
	v_pk_add_f32 v[40:41], v[40:41], v[54:55] neg_lo:[0,1] neg_hi:[0,1]
	v_mul_f32_e32 v24, 0x3f3504f3, v13
	v_pk_fma_f32 v[12:13], v[12:13], s[56:57], v[24:25] op_sel_hi:[0,1,0]
	v_pk_add_f32 v[24:25], v[14:15], v[26:27]
	v_pk_add_f32 v[14:15], v[14:15], v[26:27] neg_lo:[0,1] neg_hi:[0,1]
	v_pk_fma_f32 v[52:53], v[52:53], s[56:57], v[66:67] op_sel:[1,0,0] op_sel_hi:[1,1,0]
	v_pk_mul_f32 v[26:27], v[14:15], s[66:67] op_sel_hi:[0,1]
	v_pk_fma_f32 v[14:15], v[14:15], s[40:41], v[26:27] op_sel:[1,0,0]
	v_pk_add_f32 v[26:27], v[4:5], v[16:17]
	v_pk_add_f32 v[4:5], v[4:5], v[16:17] neg_lo:[0,1] neg_hi:[0,1]
	v_xor_b32_e32 v55, 0x80000000, v40
	v_xor_b32_e32 v17, 0x80000000, v4
	v_mov_b32_e32 v16, v5
	v_pk_add_f32 v[4:5], v[6:7], v[18:19]
	v_pk_add_f32 v[6:7], v[6:7], v[18:19] neg_lo:[0,1] neg_hi:[0,1]
	v_mov_b32_e32 v54, v41
	v_pk_mul_f32 v[18:19], v[6:7], s[44:45] op_sel_hi:[0,1]
	v_pk_fma_f32 v[6:7], v[6:7], s[42:43], v[18:19] op_sel:[1,0,0]
	s_waitcnt lgkmcnt(0)
	v_pk_add_f32 v[18:19], v[0:1], v[8:9]
	v_pk_add_f32 v[0:1], v[0:1], v[8:9] neg_lo:[0,1] neg_hi:[0,1]
	v_pk_add_f32 v[40:41], v[150:151], v[138:139]
	v_mul_f32_e32 v8, 0xbf3504f3, v0
	v_pk_fma_f32 v[0:1], v[0:1], s[56:57], v[8:9] op_sel:[1,0,0] op_sel_hi:[1,1,0]
	v_pk_add_f32 v[8:9], v[2:3], v[10:11]
	v_pk_add_f32 v[2:3], v[2:3], v[10:11] neg_lo:[0,1] neg_hi:[0,1]
	v_pk_add_f32 v[138:139], v[150:151], v[138:139] neg_lo:[0,1] neg_hi:[0,1]
	v_pk_mul_f32 v[10:11], v[2:3], s[58:59] op_sel_hi:[0,1]
	v_pk_fma_f32 v[2:3], v[2:3], s[66:67], v[10:11] op_sel:[1,0,0]
	v_pk_add_f32 v[10:11], v[48:49], v[26:27]
	v_pk_add_f32 v[26:27], v[48:49], v[26:27] neg_lo:[0,1] neg_hi:[0,1]
	v_pk_add_f32 v[48:49], v[28:29], v[4:5]
	v_pk_add_f32 v[4:5], v[28:29], v[4:5] neg_lo:[0,1] neg_hi:[0,1]
	v_pk_add_f32 v[150:151], v[146:147], v[50:51]
	v_mul_f32_e32 v28, 0x3f3504f3, v5
	v_pk_fma_f32 v[4:5], v[4:5], s[56:57], v[28:29] op_sel_hi:[0,1,0]
	v_pk_add_f32 v[28:29], v[30:31], v[18:19]
	v_pk_add_f32 v[18:19], v[30:31], v[18:19] neg_lo:[0,1] neg_hi:[0,1]
	v_pk_add_f32 v[50:51], v[146:147], v[50:51] neg_lo:[0,1] neg_hi:[0,1]
	v_xor_b32_e32 v31, 0x80000000, v18
	v_mov_b32_e32 v30, v19
	v_pk_add_f32 v[18:19], v[24:25], v[8:9]
	v_pk_add_f32 v[8:9], v[24:25], v[8:9] neg_lo:[0,1] neg_hi:[0,1]
	v_ashrrev_i32_e32 v33, 31, v32
	v_mul_f32_e32 v24, 0xbf3504f3, v8
	v_pk_fma_f32 v[8:9], v[8:9], s[56:57], v[24:25] op_sel:[1,0,0] op_sel_hi:[1,1,0]
	v_pk_add_f32 v[24:25], v[20:21], v[16:17]
	v_pk_add_f32 v[16:17], v[20:21], v[16:17] neg_lo:[0,1] neg_hi:[0,1]
	v_pk_add_f32 v[20:21], v[22:23], v[6:7]
	v_pk_add_f32 v[6:7], v[22:23], v[6:7] neg_lo:[0,1] neg_hi:[0,1]
	v_xor_b32_e32 v147, 0x80000000, v50
	v_mul_f32_e32 v22, 0x3f3504f3, v7
	v_pk_fma_f32 v[6:7], v[6:7], s[56:57], v[22:23] op_sel_hi:[0,1,0]
	v_pk_add_f32 v[22:23], v[12:13], v[0:1]
	v_pk_add_f32 v[0:1], v[12:13], v[0:1] neg_lo:[0,1] neg_hi:[0,1]
	v_mov_b32_e32 v146, v51
	v_xor_b32_e32 v13, 0x80000000, v0
	v_mov_b32_e32 v12, v1
	v_pk_add_f32 v[0:1], v[14:15], v[2:3]
	v_pk_add_f32 v[2:3], v[14:15], v[2:3] neg_lo:[0,1] neg_hi:[0,1]
	v_pk_add_f32 v[50:51], v[36:37], v[140:141]
	v_mul_f32_e32 v14, 0xbf3504f3, v2
	v_pk_fma_f32 v[2:3], v[2:3], s[56:57], v[14:15] op_sel:[1,0,0] op_sel_hi:[1,1,0]
	v_pk_add_f32 v[14:15], v[10:11], v[28:29]
	v_pk_add_f32 v[10:11], v[10:11], v[28:29] neg_lo:[0,1] neg_hi:[0,1]
	v_pk_add_f32 v[28:29], v[48:49], v[18:19]
	v_pk_add_f32 v[18:19], v[48:49], v[18:19] neg_lo:[0,1] neg_hi:[0,1]
	v_pk_add_f32 v[36:37], v[36:37], v[140:141] neg_lo:[0,1] neg_hi:[0,1]
	v_xor_b32_e32 v49, 0x80000000, v18
	v_mov_b32_e32 v48, v19
	v_pk_add_f32 v[18:19], v[26:27], v[30:31]
	v_pk_add_f32 v[26:27], v[26:27], v[30:31] neg_lo:[0,1] neg_hi:[0,1]
	v_pk_add_f32 v[30:31], v[4:5], v[8:9]
	v_pk_add_f32 v[4:5], v[4:5], v[8:9] neg_lo:[0,1] neg_hi:[0,1]
	v_pk_add_f32 v[140:141], v[46:47], v[52:53]
	v_xor_b32_e32 v9, 0x80000000, v4
	v_mov_b32_e32 v8, v5
	v_pk_add_f32 v[4:5], v[24:25], v[22:23]
	v_pk_add_f32 v[22:23], v[24:25], v[22:23] neg_lo:[0,1] neg_hi:[0,1]
	v_pk_add_f32 v[24:25], v[20:21], v[0:1]
	v_pk_add_f32 v[0:1], v[20:21], v[0:1] neg_lo:[0,1] neg_hi:[0,1]
	v_pk_add_f32 v[156:157], v[136:137], v[144:145]
	v_xor_b32_e32 v21, 0x80000000, v0
	v_mov_b32_e32 v20, v1
	v_pk_add_f32 v[0:1], v[16:17], v[12:13]
	v_pk_add_f32 v[12:13], v[16:17], v[12:13] neg_lo:[0,1] neg_hi:[0,1]
	v_pk_add_f32 v[16:17], v[6:7], v[2:3]
	v_pk_add_f32 v[2:3], v[6:7], v[2:3] neg_lo:[0,1] neg_hi:[0,1]
	v_pk_add_f32 v[158:159], v[136:137], v[144:145] neg_lo:[0,1] neg_hi:[0,1]
	v_xor_b32_e32 v7, 0x80000000, v2
	v_mov_b32_e32 v6, v3
	v_lshl_add_u64 v[136:137], v[32:33], 3, s[86:87]
	v_pk_add_f32 v[174:175], v[50:51], v[140:141]
	v_pk_add_f32 v[176:177], v[50:51], v[140:141] neg_lo:[0,1] neg_hi:[0,1]
	v_pk_add_f32 v[50:51], v[14:15], v[28:29]
	v_pk_add_f32 v[178:179], v[14:15], v[28:29] neg_lo:[0,1] neg_hi:[0,1]
	v_pk_add_f32 v[180:181], v[10:11], v[48:49]
	v_pk_add_f32 v[182:183], v[10:11], v[48:49] neg_lo:[0,1] neg_hi:[0,1]
	v_pk_add_f32 v[188:189], v[26:27], v[8:9]
	v_pk_add_f32 v[190:191], v[26:27], v[8:9] neg_lo:[0,1] neg_hi:[0,1]
	v_pk_add_f32 v[192:193], v[4:5], v[24:25]
	v_pk_add_f32 v[194:195], v[4:5], v[24:25] neg_lo:[0,1] neg_hi:[0,1]
	v_pk_add_f32 v[220:221], v[0:1], v[16:17]
	v_pk_add_f32 v[222:223], v[0:1], v[16:17] neg_lo:[0,1] neg_hi:[0,1]
	v_pk_add_f32 v[224:225], v[12:13], v[6:7]
	v_pk_add_f32 v[226:227], v[12:13], v[6:7] neg_lo:[0,1] neg_hi:[0,1]
	global_load_dwordx4 v[0:3], v[136:137], off offset:48
	global_load_dwordx4 v[4:7], v[136:137], off offset:32
	global_load_dwordx4 v[8:11], v[136:137], off offset:16
	global_load_dwordx4 v[12:15], v[136:137], off
	v_pk_add_f32 v[46:47], v[46:47], v[52:53] neg_lo:[0,1] neg_hi:[0,1]
	v_ashrrev_i32_e32 v35, 31, v34
	v_xor_b32_e32 v53, 0x80000000, v46
	v_mov_b32_e32 v52, v47
	v_pk_add_f32 v[46:47], v[142:143], v[152:153]
	v_pk_add_f32 v[142:143], v[142:143], v[152:153] neg_lo:[0,1] neg_hi:[0,1]
	v_lshl_add_u64 v[152:153], v[34:35], 3, s[86:87]
	v_pk_add_f32 v[184:185], v[18:19], v[30:31]
	v_pk_add_f32 v[186:187], v[18:19], v[30:31] neg_lo:[0,1] neg_hi:[0,1]
	v_pk_add_f32 v[216:217], v[22:23], v[20:21]
	v_pk_add_f32 v[218:219], v[22:23], v[20:21] neg_lo:[0,1] neg_hi:[0,1]
	v_pk_add_f32 v[164:165], v[38:39], v[54:55]
	v_pk_add_f32 v[54:55], v[38:39], v[54:55] neg_lo:[0,1] neg_hi:[0,1]
	v_pk_add_f32 v[170:171], v[138:139], v[146:147]
	v_pk_add_f32 v[172:173], v[138:139], v[146:147] neg_lo:[0,1] neg_hi:[0,1]
	v_pk_add_f32 v[38:39], v[36:37], v[52:53]
	v_pk_add_f32 v[36:37], v[36:37], v[52:53] neg_lo:[0,1] neg_hi:[0,1]
	v_pk_add_f32 v[166:167], v[40:41], v[150:151]
	v_pk_add_f32 v[40:41], v[40:41], v[150:151] neg_lo:[0,1] neg_hi:[0,1]
	v_cmp_lt_i32_e32 vcc, -1, v42
	v_add_u32_e32 v42, 0x400, v42
	s_or_b64 s[92:93], vcc, s[92:93]
	s_waitcnt vmcnt(0)
	v_xor_b32_e32 v16, 0x80000000, v13
	v_mov_b32_e32 v17, v12
	v_pk_mul_f32 v[16:17], v[46:47], v[16:17] op_sel:[1,0]
	s_nop 0
	v_pk_fma_f32 v[12:13], v[12:13], v[46:47], v[16:17] op_sel_hi:[1,0,1]
	v_pk_fma_f32 v[12:13], v[46:47], v[252:253], v[12:13]
	global_load_dwordx4 v[16:19], v[152:153], off offset:48
	global_load_dwordx4 v[20:23], v[152:153], off offset:32
	global_load_dwordx4 v[24:27], v[152:153], off offset:16
	global_load_dwordx4 v[28:31], v[152:153], off
	s_waitcnt vmcnt(0)
	v_xor_b32_e32 v32, 0x80000000, v29
	v_mov_b32_e32 v33, v28
	v_pk_mul_f32 v[32:33], v[50:51], v[32:33] op_sel:[1,0]
	s_nop 0
	v_pk_fma_f32 v[28:29], v[28:29], v[50:51], v[32:33] op_sel_hi:[1,0,1]
	v_pk_fma_f32 v[28:29], v[50:51], v[252:253], v[28:29]
	ds_write_b64 v43, v[12:13]
	ds_write_b64 v44, v[28:29]
	global_load_dwordx4 v[32:35], v[136:137], off offset:112
	global_load_dwordx4 v[46:49], v[136:137], off offset:96
	global_load_dwordx4 v[50:53], v[136:137], off offset:80
	s_nop 0
	global_load_dwordx4 v[136:139], v[136:137], off offset:64
	s_waitcnt vmcnt(0)
	v_xor_b32_e32 v12, 0x80000000, v137
	v_mov_b32_e32 v13, v136
	v_pk_mul_f32 v[12:13], v[142:143], v[12:13] op_sel:[1,0]
	s_nop 0
	v_pk_fma_f32 v[12:13], v[142:143], v[136:137], v[12:13] op_sel_hi:[0,1,1]
	v_pk_fma_f32 v[12:13], v[142:143], v[252:253], v[12:13]
	global_load_dwordx4 v[140:143], v[152:153], off offset:112
	global_load_dwordx4 v[144:147], v[152:153], off offset:96
	global_load_dwordx4 v[148:151], v[152:153], off offset:80
	s_nop 0
	global_load_dwordx4 v[152:155], v[152:153], off offset:64
	s_waitcnt vmcnt(0)
	v_xor_b32_e32 v28, 0x80000000, v153
	v_mov_b32_e32 v29, v152
	v_pk_mul_f32 v[28:29], v[178:179], v[28:29] op_sel:[1,0]
	s_nop 0
	v_pk_fma_f32 v[28:29], v[178:179], v[152:153], v[28:29] op_sel_hi:[0,1,1]
	v_pk_fma_f32 v[28:29], v[178:179], v[252:253], v[28:29]
	ds_write_b64 v43, v[12:13] offset:64
	ds_write_b64 v44, v[28:29] offset:64
	v_xor_b32_e32 v12, 0x80000000, v5
	v_mov_b32_e32 v13, v4
	v_pk_mul_f32 v[12:13], v[156:157], v[12:13] op_sel:[1,0]
	s_nop 0
	v_pk_fma_f32 v[4:5], v[156:157], v[4:5], v[12:13] op_sel_hi:[0,1,1]
	v_pk_fma_f32 v[4:5], v[156:157], v[252:253], v[4:5]
	v_xor_b32_e32 v12, 0x80000000, v21
	v_mov_b32_e32 v13, v20
	v_pk_mul_f32 v[12:13], v[180:181], v[12:13] op_sel:[1,0]
	s_nop 0
	v_pk_fma_f32 v[12:13], v[180:181], v[20:21], v[12:13] op_sel_hi:[0,1,1]
	v_pk_fma_f32 v[12:13], v[180:181], v[252:253], v[12:13]
	ds_write_b64 v43, v[4:5] offset:32
	ds_write_b64 v44, v[12:13] offset:32
	v_xor_b32_e32 v4, 0x80000000, v47
	v_mov_b32_e32 v5, v46
	v_pk_mul_f32 v[4:5], v[158:159], v[4:5] op_sel:[1,0]
	v_xor_b32_e32 v12, 0x80000000, v145
	v_mov_b32_e32 v13, v144
	v_pk_fma_f32 v[4:5], v[158:159], v[46:47], v[4:5] op_sel_hi:[0,1,1]
	v_pk_fma_f32 v[4:5], v[158:159], v[252:253], v[4:5]
	v_pk_mul_f32 v[12:13], v[182:183], v[12:13] op_sel:[1,0]
	s_nop 0
	v_pk_fma_f32 v[12:13], v[182:183], v[144:145], v[12:13] op_sel_hi:[0,1,1]
	v_pk_fma_f32 v[12:13], v[182:183], v[252:253], v[12:13]
	ds_write_b64 v43, v[4:5] offset:96
	ds_write_b64 v44, v[12:13] offset:96
	v_xor_b32_e32 v4, 0x80000000, v9
	v_mov_b32_e32 v5, v8
	v_pk_mul_f32 v[4:5], v[160:161], v[4:5] op_sel:[1,0]
	s_nop 0
	v_pk_fma_f32 v[4:5], v[160:161], v[8:9], v[4:5] op_sel_hi:[0,1,1]
	v_pk_fma_f32 v[4:5], v[160:161], v[252:253], v[4:5]
	v_xor_b32_e32 v8, 0x80000000, v25
	v_mov_b32_e32 v9, v24
	v_pk_mul_f32 v[8:9], v[184:185], v[8:9] op_sel:[1,0]
	s_nop 0
	v_pk_fma_f32 v[8:9], v[184:185], v[24:25], v[8:9] op_sel_hi:[0,1,1]
	v_pk_fma_f32 v[8:9], v[184:185], v[252:253], v[8:9]
	ds_write_b64 v43, v[4:5] offset:16
	ds_write_b64 v44, v[8:9] offset:16
	v_xor_b32_e32 v4, 0x80000000, v51
	v_mov_b32_e32 v5, v50
	v_pk_mul_f32 v[4:5], v[162:163], v[4:5] op_sel:[1,0]
	v_xor_b32_e32 v8, 0x80000000, v149
	v_mov_b32_e32 v9, v148
	v_pk_fma_f32 v[4:5], v[162:163], v[50:51], v[4:5] op_sel_hi:[0,1,1]
	v_pk_fma_f32 v[4:5], v[162:163], v[252:253], v[4:5]
	v_pk_mul_f32 v[8:9], v[186:187], v[8:9] op_sel:[1,0]
	s_nop 0
	v_pk_fma_f32 v[8:9], v[186:187], v[148:149], v[8:9] op_sel_hi:[0,1,1]
	v_pk_fma_f32 v[8:9], v[186:187], v[252:253], v[8:9]
	ds_write_b64 v43, v[4:5] offset:80
	ds_write_b64 v44, v[8:9] offset:80
	v_xor_b32_e32 v4, 0x80000000, v1
	v_mov_b32_e32 v5, v0
	v_pk_mul_f32 v[4:5], v[164:165], v[4:5] op_sel:[1,0]
	s_nop 0
	v_pk_fma_f32 v[0:1], v[164:165], v[0:1], v[4:5] op_sel_hi:[0,1,1]
	v_pk_fma_f32 v[0:1], v[164:165], v[252:253], v[0:1]
	v_xor_b32_e32 v4, 0x80000000, v17
	v_mov_b32_e32 v5, v16
	v_pk_mul_f32 v[4:5], v[188:189], v[4:5] op_sel:[1,0]
	s_nop 0
	v_pk_fma_f32 v[4:5], v[188:189], v[16:17], v[4:5] op_sel_hi:[0,1,1]
	v_pk_fma_f32 v[4:5], v[188:189], v[252:253], v[4:5]
	ds_write_b64 v43, v[0:1] offset:48
	ds_write_b64 v44, v[4:5] offset:48
	v_xor_b32_e32 v0, 0x80000000, v33
	v_mov_b32_e32 v1, v32
	v_pk_mul_f32 v[0:1], v[54:55], v[0:1] op_sel:[1,0]
	v_xor_b32_e32 v4, 0x80000000, v141
	v_mov_b32_e32 v5, v140
	v_pk_fma_f32 v[0:1], v[54:55], v[32:33], v[0:1] op_sel_hi:[0,1,1]
	v_pk_fma_f32 v[0:1], v[54:55], v[252:253], v[0:1]
	v_pk_mul_f32 v[4:5], v[190:191], v[4:5] op_sel:[1,0]
	s_nop 0
	v_pk_fma_f32 v[4:5], v[190:191], v[140:141], v[4:5] op_sel_hi:[0,1,1]
	v_pk_fma_f32 v[4:5], v[190:191], v[252:253], v[4:5]
	ds_write_b64 v43, v[0:1] offset:112
	ds_write_b64 v44, v[4:5] offset:112
	v_xor_b32_e32 v0, 0x80000000, v15
	v_mov_b32_e32 v1, v14
	v_pk_mul_f32 v[0:1], v[166:167], v[0:1] op_sel:[1,0]
	v_xor_b32_e32 v4, 0x80000000, v31
	v_mov_b32_e32 v5, v30
	v_pk_fma_f32 v[0:1], v[166:167], v[14:15], v[0:1] op_sel_hi:[0,1,1]
	v_pk_fma_f32 v[0:1], v[166:167], v[252:253], v[0:1]
	v_pk_mul_f32 v[4:5], v[192:193], v[4:5] op_sel:[1,0]
	s_nop 0
	v_pk_fma_f32 v[4:5], v[192:193], v[30:31], v[4:5] op_sel_hi:[0,1,1]
	v_pk_fma_f32 v[4:5], v[192:193], v[252:253], v[4:5]
	ds_write_b64 v43, v[0:1] offset:8
	ds_write_b64 v44, v[4:5] offset:8
	v_xor_b32_e32 v0, 0x80000000, v139
	v_mov_b32_e32 v1, v138
	v_pk_mul_f32 v[0:1], v[40:41], v[0:1] op_sel:[1,0]
	v_xor_b32_e32 v4, 0x80000000, v155
	v_mov_b32_e32 v5, v154
	v_pk_fma_f32 v[0:1], v[40:41], v[138:139], v[0:1] op_sel_hi:[0,1,1]
	v_pk_fma_f32 v[0:1], v[40:41], v[252:253], v[0:1]
	v_pk_mul_f32 v[4:5], v[194:195], v[4:5] op_sel:[1,0]
	s_nop 0
	v_pk_fma_f32 v[4:5], v[194:195], v[154:155], v[4:5] op_sel_hi:[0,1,1]
	v_pk_fma_f32 v[4:5], v[194:195], v[252:253], v[4:5]
	ds_write_b64 v43, v[0:1] offset:72
	ds_write_b64 v44, v[4:5] offset:72
	v_xor_b32_e32 v0, 0x80000000, v7
	v_mov_b32_e32 v1, v6
	v_pk_mul_f32 v[0:1], v[170:171], v[0:1] op_sel:[1,0]
	v_xor_b32_e32 v4, 0x80000000, v23
	v_mov_b32_e32 v5, v22
	v_pk_fma_f32 v[0:1], v[170:171], v[6:7], v[0:1] op_sel_hi:[0,1,1]
	v_pk_fma_f32 v[0:1], v[170:171], v[252:253], v[0:1]
	v_pk_mul_f32 v[4:5], v[216:217], v[4:5] op_sel:[1,0]
	s_nop 0
	v_pk_fma_f32 v[4:5], v[216:217], v[22:23], v[4:5] op_sel_hi:[0,1,1]
	v_pk_fma_f32 v[4:5], v[216:217], v[252:253], v[4:5]
	ds_write_b64 v43, v[0:1] offset:40
	ds_write_b64 v44, v[4:5] offset:40
	v_xor_b32_e32 v0, 0x80000000, v49
	v_mov_b32_e32 v1, v48
	v_pk_mul_f32 v[0:1], v[172:173], v[0:1] op_sel:[1,0]
	v_xor_b32_e32 v4, 0x80000000, v147
	v_mov_b32_e32 v5, v146
	v_pk_fma_f32 v[0:1], v[172:173], v[48:49], v[0:1] op_sel_hi:[0,1,1]
	v_pk_fma_f32 v[0:1], v[172:173], v[252:253], v[0:1]
	v_pk_mul_f32 v[4:5], v[218:219], v[4:5] op_sel:[1,0]
	s_nop 0
	v_pk_fma_f32 v[4:5], v[218:219], v[146:147], v[4:5] op_sel_hi:[0,1,1]
	v_pk_fma_f32 v[4:5], v[218:219], v[252:253], v[4:5]
	ds_write_b64 v43, v[0:1] offset:104
	ds_write_b64 v44, v[4:5] offset:104
	v_xor_b32_e32 v0, 0x80000000, v11
	v_mov_b32_e32 v1, v10
	v_pk_mul_f32 v[0:1], v[174:175], v[0:1] op_sel:[1,0]
	v_xor_b32_e32 v4, 0x80000000, v27
	v_mov_b32_e32 v5, v26
	v_pk_fma_f32 v[0:1], v[174:175], v[10:11], v[0:1] op_sel_hi:[0,1,1]
	v_pk_fma_f32 v[0:1], v[174:175], v[252:253], v[0:1]
	v_pk_mul_f32 v[4:5], v[220:221], v[4:5] op_sel:[1,0]
	s_nop 0
	v_pk_fma_f32 v[4:5], v[220:221], v[26:27], v[4:5] op_sel_hi:[0,1,1]
	v_pk_fma_f32 v[4:5], v[220:221], v[252:253], v[4:5]
	ds_write_b64 v43, v[0:1] offset:24
	ds_write_b64 v44, v[4:5] offset:24
	v_xor_b32_e32 v0, 0x80000000, v53
	v_mov_b32_e32 v1, v52
	v_pk_mul_f32 v[0:1], v[176:177], v[0:1] op_sel:[1,0]
	v_xor_b32_e32 v4, 0x80000000, v151
	v_mov_b32_e32 v5, v150
	v_pk_fma_f32 v[0:1], v[176:177], v[52:53], v[0:1] op_sel_hi:[0,1,1]
	v_pk_fma_f32 v[0:1], v[176:177], v[252:253], v[0:1]
	v_pk_mul_f32 v[4:5], v[222:223], v[4:5] op_sel:[1,0]
	s_nop 0
	v_pk_fma_f32 v[4:5], v[222:223], v[150:151], v[4:5] op_sel_hi:[0,1,1]
	v_pk_fma_f32 v[4:5], v[222:223], v[252:253], v[4:5]
	ds_write_b64 v43, v[0:1] offset:88
	ds_write_b64 v44, v[4:5] offset:88
	v_xor_b32_e32 v0, 0x80000000, v3
	v_mov_b32_e32 v1, v2
	v_pk_mul_f32 v[0:1], v[38:39], v[0:1] op_sel:[1,0]
	s_nop 0
	v_pk_fma_f32 v[0:1], v[38:39], v[2:3], v[0:1] op_sel_hi:[0,1,1]
	v_pk_fma_f32 v[0:1], v[38:39], v[252:253], v[0:1]
	v_xor_b32_e32 v2, 0x80000000, v19
	v_mov_b32_e32 v3, v18
	v_pk_mul_f32 v[2:3], v[224:225], v[2:3] op_sel:[1,0]
	s_nop 0
	v_pk_fma_f32 v[2:3], v[224:225], v[18:19], v[2:3] op_sel_hi:[0,1,1]
	v_pk_fma_f32 v[2:3], v[224:225], v[252:253], v[2:3]
	ds_write_b64 v43, v[0:1] offset:56
	ds_write_b64 v44, v[2:3] offset:56
	v_xor_b32_e32 v0, 0x80000000, v35
	v_mov_b32_e32 v1, v34
	v_pk_mul_f32 v[0:1], v[36:37], v[0:1] op_sel:[1,0]
	v_xor_b32_e32 v2, 0x80000000, v143
	v_mov_b32_e32 v3, v142
	v_pk_fma_f32 v[0:1], v[36:37], v[34:35], v[0:1] op_sel_hi:[0,1,1]
	v_pk_fma_f32 v[0:1], v[36:37], v[252:253], v[0:1]
	v_pk_mul_f32 v[2:3], v[226:227], v[2:3] op_sel:[1,0]
	s_nop 0
	v_pk_fma_f32 v[2:3], v[226:227], v[142:143], v[2:3] op_sel_hi:[0,1,1]
	v_pk_fma_f32 v[2:3], v[226:227], v[252:253], v[2:3]
	ds_write_b64 v43, v[0:1] offset:120
	ds_write_b64 v44, v[2:3] offset:120
	s_andn2_b64 exec, exec, s[92:93]
	s_cbranch_execnz .LBB0_353

.LBB0_366:
	s_or_b64 exec, exec, s[90:91]
	s_waitcnt lgkmcnt(0)
	s_barrier
	ds_read2_b64 v[0:3], v214 offset1:1
	ds_read2_b64 v[4:7], v214 offset0:2 offset1:3
	ds_read2_b64 v[8:11], v214 offset0:4 offset1:5
	ds_read2_b64 v[12:15], v214 offset0:6 offset1:7
	ds_read2_b64 v[16:19], v215 offset1:1
	ds_read2_b64 v[20:23], v215 offset0:2 offset1:3
	ds_read2_b64 v[24:27], v215 offset0:4 offset1:5
	ds_read2_b64 v[28:31], v215 offset0:6 offset1:7
	s_lshl_b32 s33, s80, 11
	s_add_i32 s40, s33, s82
	s_ashr_i32 s41, s40, 31
	s_lshl_b64 s[40:41], s[40:41], 14
	s_add_u32 s92, s8, s40
	s_addc_u32 s93, s9, s41
	s_add_u32 s90, s92, 0x1000000
	s_addc_u32 s91, s93, 0
	v_lshlrev_b64 v[32:33], 1, v[62:63]
	v_lshlrev_b64 v[34:35], 1, v[70:71]
	v_lshl_add_u64 v[36:37], s[92:93], 0, v[32:33]
	v_lshl_add_u64 v[38:39], s[90:91], 0, v[32:33]
	v_lshl_add_u64 v[40:41], s[92:93], 0, v[34:35]
	v_lshl_add_u64 v[42:43], s[90:91], 0, v[34:35]
	s_waitcnt lgkmcnt(4)
	v_cvt_pk_bf16_f32 v136, v0, v2
	v_cvt_pk_bf16_f32 v137, v4, v6
	v_cvt_pk_bf16_f32 v138, v8, v10
	v_cvt_pk_bf16_f32 v139, v12, v14
	v_cvt_pk_bf16_f32 v140, v1, v3
	v_cvt_pk_bf16_f32 v141, v5, v7
	v_cvt_pk_bf16_f32 v142, v9, v11
	v_cvt_pk_bf16_f32 v143, v13, v15
	global_store_dwordx4 v[36:37], v[136:139], off
	global_store_dwordx4 v[38:39], v[140:143], off
	s_waitcnt lgkmcnt(0)
	v_cvt_pk_bf16_f32 v144, v16, v18
	v_cvt_pk_bf16_f32 v145, v20, v22
	v_cvt_pk_bf16_f32 v146, v24, v26
	v_cvt_pk_bf16_f32 v147, v28, v30
	v_cvt_pk_bf16_f32 v150, v17, v19
	v_cvt_pk_bf16_f32 v151, v21, v23
	v_cvt_pk_bf16_f32 v152, v25, v27
	v_cvt_pk_bf16_f32 v153, v29, v31
	global_store_dwordx4 v[40:41], v[144:147], off
	global_store_dwordx4 v[42:43], v[150:153], off
	s_add_i32 s80, s80, 1
	s_cmp_eq_u32 s80, 4
	s_cbranch_scc1 .LBB0_398
	s_branch .LBB0_309
